# attention: each item processes its long causal q-block first, so the 16 workgroups sharing a head sweep the same K/V tiles together (L2 reuse)
# speedup vs baseline: 1.0229x; 1.0179x over previous
.LBB0_388:
	s_and_b64 s[4:5], s[74:75], exec
	s_cselect_b32 s8, s89, s88
	s_ashr_i32 s9, s8, 31
	s_lshl_b64 s[4:5], s[8:9], 8
	s_add_u32 s52, s4, s34
	s_addc_u32 s53, s5, s35
	s_mul_i32 s4, s53, 0x3000
	s_mul_hi_u32 s5, s52, 0x3000
	s_add_i32 s5, s5, s4
	s_mul_i32 s4, s52, 0x3000
	s_add_u32 s78, s90, s4
	s_addc_u32 s79, s91, s5
	s_lshl_b64 s[4:5], s[52:53], 7
	s_add_u32 s10, s24, s4
	s_addc_u32 s11, s25, s5
	s_add_u32 s76, s26, s4
	v_mov_b32_e32 v76, v184
	s_addc_u32 s77, s27, s5
	s_movk_i32 s4, 0x3000
	v_readfirstlane_b32 s5, v76
	s_ashr_i32 s96, s5, 6
	v_and_b32_e32 v187, 31, v76
	s_lshl_b32 s97, s96, 5
	v_lshlrev_b32_e32 v78, 3, v76
	v_bfe_u32 v188, v76, 5, 1
	v_and_b32_e32 v185, 0x78, v78
	v_lshlrev_b32_e32 v80, 4, v76
	v_or_b32_e32 v2, s97, v187
	v_ashrrev_i32_e32 v77, 4, v76
	v_lshlrev_b32_e32 v175, 1, v185
	v_ashrrev_i32_e32 v79, 3, v76
	v_and_b32_e32 v58, 0x70, v80
	v_lshlrev_b32_e32 v59, 4, v188
	v_mul_lo_u32 v2, v2, s4
	s_lshl_b32 s4, s96, 12
	v_lshlrev_b32_e32 v3, 7, v187
	v_and_b32_e32 v4, 32, v76
	v_lshl_or_b32 v0, v77, 14, v175
	v_lshl_or_b32 v14, v79, 7, v58
	v_or_b32_e32 v2, v2, v59
	v_or3_b32 v17, v3, v4, s4
	global_load_dwordx4 v[34:37], v17, s[10:11]
	global_load_dwordx4 v[38:41], v17, s[76:77]
	global_load_dwordx4 v[42:45], v17, s[10:11] offset:16
	global_load_dwordx4 v[46:49], v17, s[76:77] offset:16
	global_load_dwordx4 v[50:53], v2, s[78:79] offset:320
	global_load_dwordx4 v[54:57], v2, s[78:79] offset:256
	v_and_b32_e32 v186, 63, v76
	s_add_i32 s4, s4, 0
	v_lshlrev_b32_e32 v15, 4, v186
	s_add_i32 s4, s4, 0x14800
	v_add_u32_e32 v195, s4, v15
	global_load_dwordx4 v[156:159], v2, s[78:79]
	global_load_dwordx4 v[152:155], v2, s[78:79] offset:32
	global_load_dwordx4 v[148:151], v2, s[78:79] offset:64
	global_load_dwordx4 v[144:147], v2, s[78:79] offset:96
	global_load_dwordx4 v[140:143], v2, s[78:79] offset:128
	global_load_dwordx4 v[136:139], v2, s[78:79] offset:160
	global_load_dwordx4 v[132:135], v2, s[78:79] offset:192
	global_load_dwordx4 v[128:131], v2, s[78:79] offset:224
	global_load_dwordx4 v[26:29], v2, s[78:79] offset:288
	global_load_dwordx4 v[30:33], v2, s[78:79] offset:352
	global_load_dwordx4 v[18:21], v0, s[36:37] offset:256
	s_nop 0
	global_load_dwordx4 v[2:5], v0, s[36:37]
	global_load_dwordx4 v[22:25], v0, s[40:41] offset:256
	global_load_dwordx4 v[10:13], v0, s[40:41]
	global_load_dwordx4 v[6:9], v14, s[38:39]
	s_lshl_b32 s6, s8, 8
	s_add_i32 s4, s97, s6
	s_waitcnt vmcnt(20)
	v_mov_b32_e32 v60, v34
	s_waitcnt vmcnt(19)
	v_mov_b32_e32 v61, v38
	v_mov_b32_e32 v63, v34
	v_mov_b32_e32 v34, v39
	s_waitcnt vmcnt(16)
	v_lshlrev_b32_e32 v69, 16, v50
	s_waitcnt vmcnt(15)
	v_lshlrev_b32_e32 v68, 16, v54
	v_and_b32_e32 v73, 0xffff0000, v50
	v_and_b32_e32 v72, 0xffff0000, v54
	v_mov_b32_e32 v62, v38
	v_mov_b32_e32 v64, v42
	v_mov_b32_e32 v67, v42
	v_mov_b32_e32 v38, v35
	v_mov_b32_e32 v42, v47
	v_and_b32_e32 v75, 0xffff0000, v52
	v_and_b32_e32 v74, 0xffff0000, v56
	v_pk_mul_f32 v[60:61], v[60:61], v[68:69]
	v_pk_mul_f32 v[34:35], v[34:35], v[72:73]
	v_pk_mul_f32 v[38:39], v[38:39], v[72:73]
	v_sub_f32_e32 v50, v60, v61
	v_add_f32_e32 v61, v35, v34
	v_pk_mul_f32 v[34:35], v[42:43], v[74:75]
	v_sub_f32_e32 v60, v38, v39
	v_add_f32_e32 v42, v35, v34
	v_lshlrev_b32_e32 v35, 16, v51
	v_lshlrev_b32_e32 v34, 16, v55
	v_mov_b32_e32 v38, v36
	v_mov_b32_e32 v39, v40
	v_pk_mul_f32 v[38:39], v[38:39], v[34:35]
	v_mov_b32_e32 v65, v46
	v_mov_b32_e32 v66, v46
	v_mov_b32_e32 v46, v43
	v_sub_f32_e32 v43, v38, v39
	v_mov_b32_e32 v38, v40
	v_mov_b32_e32 v39, v36
	v_pk_mul_f32 v[46:47], v[46:47], v[74:75]
	v_pk_mul_f32 v[34:35], v[38:39], v[34:35]
	v_sub_f32_e32 v46, v46, v47
	v_add_f32_e32 v47, v35, v34
	v_lshlrev_b32_e32 v35, 16, v53
	v_lshlrev_b32_e32 v34, 16, v57
	v_mov_b32_e32 v38, v44
	v_mov_b32_e32 v39, v48
	v_pk_mul_f32 v[62:63], v[62:63], v[68:69]
	v_pk_mul_f32 v[38:39], v[38:39], v[34:35]
	v_lshlrev_b32_e32 v71, 16, v52
	v_add_f32_e32 v52, v63, v62
	v_sub_f32_e32 v62, v38, v39
	v_mov_b32_e32 v38, v48
	v_mov_b32_e32 v39, v44
	v_pk_mul_f32 v[34:35], v[38:39], v[34:35]
	v_mov_b32_e32 v40, v37
	v_add_f32_e32 v63, v35, v34
	v_and_b32_e32 v35, 0xffff0000, v51
	v_and_b32_e32 v34, 0xffff0000, v55
	v_mov_b32_e32 v36, v41
	v_pk_mul_f32 v[38:39], v[40:41], v[34:35]
	v_pk_mul_f32 v[34:35], v[36:37], v[34:35]
	v_sub_f32_e32 v38, v38, v39
	v_add_f32_e32 v39, v35, v34
	v_and_b32_e32 v35, 0xffff0000, v53
	v_and_b32_e32 v34, 0xffff0000, v57
	v_mov_b32_e32 v48, v45
	v_lshlrev_b32_e32 v70, 16, v56
	v_pk_mul_f32 v[36:37], v[48:49], v[34:35]
	v_mov_b32_e32 v44, v49
	v_pk_mul_f32 v[64:65], v[64:65], v[70:71]
	v_sub_f32_e32 v37, v36, v37
	v_pk_mul_f32 v[34:35], v[44:45], v[34:35]
	v_pk_mul_f32 v[66:67], v[66:67], v[70:71]
	v_sub_f32_e32 v54, v64, v65
	v_add_f32_e32 v40, v35, v34
	v_cvt_pk_bf16_f32 v34, v50, v60
	v_cvt_pk_bf16_f32 v35, v43, v38
	v_cvt_pk_bf16_f32 v36, v54, v46
	v_cvt_pk_bf16_f32 v37, v62, v37
	v_add_f32_e32 v56, v67, v66
	ds_write_b128 v195, v[34:37]
	v_cvt_pk_bf16_f32 v34, v52, v61
	v_cvt_pk_bf16_f32 v35, v47, v39
	v_cvt_pk_bf16_f32 v36, v56, v42
	v_cvt_pk_bf16_f32 v37, v63, v40
	global_load_dwordx4 v[38:41], v17, s[10:11] offset:64
	global_load_dwordx4 v[42:45], v17, s[76:77] offset:64
	global_load_dwordx4 v[46:49], v17, s[10:11] offset:80
	global_load_dwordx4 v[50:53], v17, s[76:77] offset:80
	v_and_b32_e32 v55, 0xfffff0, v77
	v_lshlrev_b32_e32 v56, 1, v77
	v_and_or_b32 v55, v56, 8, v55
	v_add_u32_e32 v61, 32, v77
	v_lshrrev_b32_e32 v56, 1, v77
	v_lshrrev_b32_e32 v55, 1, v55
	v_bfe_u32 v57, v78, 5, 2
	v_and_b32_e32 v60, 3, v77
	v_and_b32_e32 v62, 0xfffff0, v61
	v_lshlrev_b32_e32 v61, 1, v61
	v_lshlrev_b32_e32 v17, 2, v188
	v_or_b32_e32 v55, v55, v57
	v_and_or_b32 v56, v56, 4, v60
	v_and_or_b32 v61, v61, 8, v62
	ds_write_b128 v195, v[34:37] offset:2048
	s_waitcnt vmcnt(9)
	v_lshlrev_b32_e32 v35, 16, v30
	v_lshlrev_b32_e32 v34, 16, v26
	v_sub_u32_e32 v54, v187, v17
	v_lshlrev_b32_e32 v55, 9, v55
	v_lshlrev_b32_e32 v56, 6, v56
	v_and_b32_e32 v60, 48, v175
	v_lshrrev_b32_e32 v61, 1, v61
	v_or_b32_e32 v57, v61, v57
	v_add_u32_e32 v193, s4, v54
	v_or3_b32 v54, v55, v56, v60
	v_lshlrev_b32_e32 v57, 9, v57
	v_or3_b32 v57, v57, v56, v60
	v_lshlrev_b32_e32 v63, 4, v79
	v_or_b32_e32 v62, 0x100, v58
	v_and_b32_e32 v63, 0x70, v63
	v_mul_lo_u32 v65, v79, s83
	v_xad_u32 v62, v62, v63, v65
	v_bitop3_b32 v61, v175, v76, s84 bitop3:0x78
	v_mul_lo_u32 v64, v77, s83
	v_add_u32_e32 v200, 0, v54
	v_add_u32_e32 v201, 0, v57
	v_add3_u32 v202, v61, v64, 0
	v_add_u32_e32 v203, 0, v62
	s_waitcnt vmcnt(3)
	v_mov_b32_e32 v36, v38
	s_waitcnt vmcnt(2)
	v_mov_b32_e32 v37, v42
	v_pk_mul_f32 v[36:37], v[36:37], v[34:35]
	s_nop 0
	v_sub_f32_e32 v55, v36, v37
	v_mov_b32_e32 v36, v42
	v_mov_b32_e32 v37, v38
	v_pk_mul_f32 v[34:35], v[36:37], v[34:35]
	s_waitcnt vmcnt(1)
	v_mov_b32_e32 v36, v46
	v_add_f32_e32 v56, v35, v34
	v_lshlrev_b32_e32 v35, 16, v32
	v_lshlrev_b32_e32 v34, 16, v28
	s_waitcnt vmcnt(0)
	v_mov_b32_e32 v37, v50
	v_pk_mul_f32 v[36:37], v[36:37], v[34:35]
	v_mov_b32_e32 v42, v39
	v_sub_f32_e32 v60, v36, v37
	v_mov_b32_e32 v36, v50
	v_mov_b32_e32 v37, v46
	v_pk_mul_f32 v[34:35], v[36:37], v[34:35]
	v_mov_b32_e32 v38, v43
	v_add_f32_e32 v63, v35, v34
	v_and_b32_e32 v35, 0xffff0000, v30
	v_and_b32_e32 v34, 0xffff0000, v26
	v_pk_mul_f32 v[36:37], v[42:43], v[34:35]
	v_pk_mul_f32 v[34:35], v[38:39], v[34:35]
	v_mov_b32_e32 v50, v47
	v_add_f32_e32 v38, v35, v34
	v_and_b32_e32 v35, 0xffff0000, v32
	v_and_b32_e32 v34, 0xffff0000, v28
	v_mov_b32_e32 v46, v51
	v_sub_f32_e32 v42, v36, v37
	v_pk_mul_f32 v[36:37], v[50:51], v[34:35]
	v_pk_mul_f32 v[34:35], v[46:47], v[34:35]
	v_sub_f32_e32 v32, v36, v37
	v_add_f32_e32 v39, v35, v34
	v_lshlrev_b32_e32 v35, 16, v31
	v_lshlrev_b32_e32 v34, 16, v27
	v_mov_b32_e32 v36, v40
	v_mov_b32_e32 v37, v44
	v_pk_mul_f32 v[36:37], v[36:37], v[34:35]
	v_and_b32_e32 v31, 0xffff0000, v31
	v_sub_f32_e32 v43, v36, v37
	v_mov_b32_e32 v36, v44
	v_mov_b32_e32 v37, v40
	v_pk_mul_f32 v[34:35], v[36:37], v[34:35]
	v_mov_b32_e32 v36, v48
	v_add_f32_e32 v46, v35, v34
	v_lshlrev_b32_e32 v35, 16, v33
	v_lshlrev_b32_e32 v34, 16, v29
	v_mov_b32_e32 v37, v52
	v_pk_mul_f32 v[36:37], v[36:37], v[34:35]
	v_and_b32_e32 v30, 0xffff0000, v27
	v_sub_f32_e32 v47, v36, v37
	v_mov_b32_e32 v36, v52
	v_mov_b32_e32 v37, v48
	v_mov_b32_e32 v44, v41
	v_pk_mul_f32 v[34:35], v[36:37], v[34:35]
	v_pk_mul_f32 v[26:27], v[44:45], v[30:31]
	v_mov_b32_e32 v40, v45
	v_add_f32_e32 v34, v35, v34
	v_sub_f32_e32 v35, v26, v27
	v_pk_mul_f32 v[26:27], v[40:41], v[30:31]
	v_mov_b32_e32 v52, v49
	v_add_f32_e32 v30, v27, v26
	v_and_b32_e32 v27, 0xffff0000, v33
	v_and_b32_e32 v26, 0xffff0000, v29
	v_pk_mul_f32 v[28:29], v[52:53], v[26:27]
	v_mov_b32_e32 v48, v53
	v_sub_f32_e32 v29, v28, v29
	v_pk_mul_f32 v[26:27], v[48:49], v[26:27]
	s_nop 0
	v_add_f32_e32 v31, v27, v26
	v_cvt_pk_bf16_f32 v26, v55, v42
	v_cvt_pk_bf16_f32 v27, v43, v35
	v_cvt_pk_bf16_f32 v28, v60, v32
	v_cvt_pk_bf16_f32 v29, v47, v29
	ds_write_b128 v195, v[26:29] offset:1024
	v_cvt_pk_bf16_f32 v26, v56, v38
	v_cvt_pk_bf16_f32 v27, v46, v30
	v_cvt_pk_bf16_f32 v28, v63, v39
	v_cvt_pk_bf16_f32 v29, v34, v31
	ds_write_b128 v195, v[26:29] offset:3072
	s_waitcnt vmcnt(0)
	ds_write_b128 v200, v[18:21]
	ds_write_b128 v201, v[22:25]
	ds_write_b128 v202, v[2:5] offset:32768
	ds_write_b128 v202, v[10:13] offset:45056
	ds_write_b128 v203, v[6:9] offset:32768
	global_load_dwordx4 v[6:9], v0, s[42:43] offset:256
	global_load_dwordx4 v[2:5], v0, s[42:43]
	global_load_dwordx4 v[54:57], v0, s[44:45] offset:256
	global_load_dwordx4 v[10:13], v0, s[44:45]
	global_load_dwordx4 v[50:53], v14, s[46:47]
	v_mul_u32_u24_e32 v84, 0x180, v187
	v_bitop3_b32 v18, v59, v80, s84 bitop3:0x78
	v_add3_u32 v196, 0, v18, v84
	s_waitcnt lgkmcnt(0)
	s_barrier
	ds_read_b128 v[18:21], v196 offset:32768
	ds_read_b128 v[60:63], v196 offset:32896
	s_waitcnt lgkmcnt(1)
	v_mfma_f32_32x32x16_bf16 v[18:33], v[18:21], v[156:159], 0
	ds_read_b128 v[34:37], v196 offset:45056
	ds_read_b128 v[64:67], v196 offset:33024
	v_bitop3_b32 v38, v59, v58, 32 bitop3:0x36
	v_add3_u32 v197, 0, v38, v84
	ds_read_b128 v[68:71], v197 offset:32768
	ds_read_b128 v[72:75], v197 offset:32896
	v_bitop3_b32 v76, v59, v58, 64 bitop3:0x36
	v_add3_u32 v199, 0, v76, v84
	s_waitcnt lgkmcnt(1)
	v_mfma_f32_32x32x16_bf16 v[18:33], v[68:71], v[152:155], v[18:33]
	ds_read_b128 v[68:71], v197 offset:45056
	ds_read_b128 v[76:79], v197 offset:33024
	s_movk_i32 s7, 0x60
	v_bitop3_b32 v58, v59, v58, s7 bitop3:0x36
	v_add3_u32 v198, 0, v58, v84
	s_cmp_gt_i32 s4, 62
	v_mfma_f32_32x32x16_bf16 v[34:49], v[34:37], v[156:159], 0
	s_waitcnt lgkmcnt(1)
	v_mfma_f32_32x32x16_bf16 v[34:49], v[68:71], v[152:155], v[34:49]
	ds_read_b128 v[68:71], v199 offset:32768
	ds_read_b128 v[80:83], v199 offset:32896
	ds_read_b128 v[84:87], v199 offset:33024
	s_waitcnt lgkmcnt(2)
	v_mfma_f32_32x32x16_bf16 v[18:33], v[68:71], v[148:151], v[18:33]
	ds_read_b128 v[68:71], v199 offset:45056
	s_waitcnt lgkmcnt(0)
	v_mfma_f32_32x32x16_bf16 v[34:49], v[68:71], v[148:151], v[34:49]
	ds_read_b128 v[68:71], v198 offset:32768
	ds_read_b128 v[88:91], v198 offset:32896
	s_waitcnt lgkmcnt(1)
	v_mfma_f32_32x32x16_bf16 v[18:33], v[68:71], v[144:147], v[18:33]
	ds_read_b128 v[68:71], v198 offset:45056
	ds_read_b128 v[92:95], v198 offset:33024
	s_waitcnt lgkmcnt(1)
	v_mfma_f32_32x32x16_bf16 v[34:49], v[68:71], v[144:147], v[34:49]
	v_mfma_f32_32x32x16_bf16 v[18:33], v[60:63], v[140:143], v[18:33]
	ds_read_b128 v[58:61], v196 offset:45184
	ds_read_b128 v[68:71], v196 offset:45312
	s_waitcnt lgkmcnt(1)
	v_mfma_f32_32x32x16_bf16 v[34:49], v[58:61], v[140:143], v[34:49]
	v_mfma_f32_32x32x16_bf16 v[18:33], v[72:75], v[136:139], v[18:33]
	ds_read_b128 v[58:61], v197 offset:45184
	ds_read_b128 v[72:75], v197 offset:45312
	s_waitcnt lgkmcnt(1)
	v_mfma_f32_32x32x16_bf16 v[34:49], v[58:61], v[136:139], v[34:49]
	v_mfma_f32_32x32x16_bf16 v[18:33], v[80:83], v[132:135], v[18:33]
	ds_read_b128 v[58:61], v199 offset:45184
	ds_read_b128 v[80:83], v199 offset:45312
	s_waitcnt lgkmcnt(1)
	v_mfma_f32_32x32x16_bf16 v[34:49], v[58:61], v[132:135], v[34:49]
	v_mfma_f32_32x32x16_bf16 v[18:33], v[88:91], v[128:131], v[18:33]
	ds_read_b128 v[58:61], v198 offset:45184
	ds_read_b128 v[88:91], v198 offset:45312
	s_waitcnt lgkmcnt(1)
	v_mfma_f32_32x32x16_bf16 v[34:49], v[58:61], v[128:131], v[34:49]
	ds_read_b128 v[58:61], v195
	ds_read_b128 v[96:99], v195 offset:1024
	s_waitcnt lgkmcnt(1)
	v_mfma_f32_32x32x16_bf16 v[18:33], v[64:67], v[58:61], v[18:33]
	v_mfma_f32_32x32x16_bf16 v[34:49], v[68:71], v[58:61], v[34:49]
	ds_read_b128 v[58:61], v195 offset:2048
	ds_read_b128 v[62:65], v195 offset:3072
	s_waitcnt lgkmcnt(2)
	v_mfma_f32_32x32x16_bf16 v[18:33], v[76:79], v[96:99], v[18:33]
	v_mfma_f32_32x32x16_bf16 v[34:49], v[72:75], v[96:99], v[34:49]
	s_waitcnt lgkmcnt(1)
	v_mfma_f32_32x32x16_bf16 v[18:33], v[84:87], v[58:61], v[18:33]
	v_mfma_f32_32x32x16_bf16 v[34:49], v[80:83], v[58:61], v[34:49]
	s_waitcnt lgkmcnt(0)
	v_mfma_f32_32x32x16_bf16 v[18:33], v[92:95], v[62:65], v[18:33]
	v_mfma_f32_32x32x16_bf16 v[34:49], v[88:91], v[62:65], v[34:49]
	s_cbranch_scc1 .LBB0_390
	v_cmp_gt_u32_e32 vcc, 2.0, v193
	v_add_u32_e32 v58, 0xbfffffe0, v193
	s_nop 7
	v_cndmask_b32_e32 v18, v16, v18, vcc
	v_cmp_lt_u32_e32 vcc, s85, v58
	v_add_u32_e32 v58, 0xbfffffff, v193
	s_nop 0
	v_cndmask_b32_e32 v34, v16, v34, vcc
	v_cmp_lt_u32_e32 vcc, s85, v58
	v_add_u32_e32 v58, 0xbfffffdf, v193
	s_nop 0
	v_cndmask_b32_e32 v19, v16, v19, vcc
	v_cmp_lt_u32_e32 vcc, s85, v58
	v_add_u32_e32 v58, 0xbffffffe, v193
	s_nop 0
	v_cndmask_b32_e32 v35, v16, v35, vcc
	v_cmp_lt_u32_e32 vcc, s85, v58
	v_add_u32_e32 v58, 0xbfffffde, v193
	s_nop 0
	v_cndmask_b32_e32 v20, v16, v20, vcc
	v_cmp_lt_u32_e32 vcc, s85, v58
	v_add_u32_e32 v58, 0xbffffffd, v193
	s_nop 0
	v_cndmask_b32_e32 v36, v16, v36, vcc
	v_cmp_lt_u32_e32 vcc, s85, v58
	v_add_u32_e32 v58, 0xbfffffdd, v193
	s_nop 0
	v_cndmask_b32_e32 v21, v16, v21, vcc
	v_cmp_lt_u32_e32 vcc, s85, v58
	v_add_u32_e32 v58, 0xbffffff8, v193
	s_nop 0
	v_cndmask_b32_e32 v37, v16, v37, vcc
	v_cmp_lt_u32_e32 vcc, s85, v58
	v_add_u32_e32 v58, 0xbfffffd8, v193
	s_nop 0
	v_cndmask_b32_e32 v22, v16, v22, vcc
	v_cmp_lt_u32_e32 vcc, s85, v58
	v_add_u32_e32 v58, 0xbffffff7, v193
	s_nop 0
	v_cndmask_b32_e32 v38, v16, v38, vcc
	v_cmp_lt_u32_e32 vcc, s85, v58
	v_add_u32_e32 v58, 0xbfffffd7, v193
	s_nop 0
	v_cndmask_b32_e32 v23, v16, v23, vcc
	v_cmp_lt_u32_e32 vcc, s85, v58
	v_add_u32_e32 v58, 0xbffffff6, v193
	s_nop 0
	v_cndmask_b32_e32 v39, v16, v39, vcc
	v_cmp_lt_u32_e32 vcc, s85, v58
	v_add_u32_e32 v58, 0xbfffffd6, v193
	s_nop 0
	v_cndmask_b32_e32 v24, v16, v24, vcc
	v_cmp_lt_u32_e32 vcc, s85, v58
	v_add_u32_e32 v58, 0xbffffff5, v193
	s_nop 0
	v_cndmask_b32_e32 v40, v16, v40, vcc
	v_cmp_lt_u32_e32 vcc, s85, v58
	v_add_u32_e32 v58, 0xbfffffd5, v193
	s_nop 0
	v_cndmask_b32_e32 v25, v16, v25, vcc
	v_cmp_lt_u32_e32 vcc, s85, v58
	v_add_u32_e32 v58, 0xbffffff0, v193
	s_nop 0
	v_cndmask_b32_e32 v41, v16, v41, vcc
	v_cmp_lt_u32_e32 vcc, s85, v58
	v_add_u32_e32 v58, 0xbfffffd0, v193
	s_nop 0
	v_cndmask_b32_e32 v26, v16, v26, vcc
	v_cmp_lt_u32_e32 vcc, s85, v58
	v_add_u32_e32 v58, 0xbfffffef, v193
	s_nop 0
	v_cndmask_b32_e32 v42, v16, v42, vcc
	v_cmp_lt_u32_e32 vcc, s85, v58
	v_add_u32_e32 v58, 0xbfffffcf, v193
	s_nop 0
	v_cndmask_b32_e32 v27, v16, v27, vcc
	v_cmp_lt_u32_e32 vcc, s85, v58
	v_add_u32_e32 v58, 0xbfffffee, v193
	s_nop 0
	v_cndmask_b32_e32 v43, v16, v43, vcc
	v_cmp_lt_u32_e32 vcc, s85, v58
	v_add_u32_e32 v58, 0xbfffffce, v193
	s_nop 0
	v_cndmask_b32_e32 v28, v16, v28, vcc
	v_cmp_lt_u32_e32 vcc, s85, v58
	v_add_u32_e32 v58, 0xbfffffed, v193
	s_nop 0
	v_cndmask_b32_e32 v44, v16, v44, vcc
	v_cmp_lt_u32_e32 vcc, s85, v58
	v_add_u32_e32 v58, 0xbfffffcd, v193
	s_nop 0
	v_cndmask_b32_e32 v29, v16, v29, vcc
	v_cmp_lt_u32_e32 vcc, s85, v58
	v_add_u32_e32 v58, 0xbfffffe8, v193
	s_nop 0
	v_cndmask_b32_e32 v45, v16, v45, vcc
	v_cmp_lt_u32_e32 vcc, s85, v58
	v_add_u32_e32 v58, 0xbfffffc8, v193
	s_nop 0
	v_cndmask_b32_e32 v30, v16, v30, vcc
	v_cmp_lt_u32_e32 vcc, s85, v58
	v_add_u32_e32 v58, 0xbfffffe7, v193
	s_nop 0
	v_cndmask_b32_e32 v46, v16, v46, vcc
	v_cmp_lt_u32_e32 vcc, s85, v58
	v_add_u32_e32 v58, 0xbfffffc7, v193
	s_nop 0
	v_cndmask_b32_e32 v31, v16, v31, vcc
	v_cmp_lt_u32_e32 vcc, s85, v58
	v_add_u32_e32 v58, 0xbfffffe6, v193
	s_nop 0
	v_cndmask_b32_e32 v47, v16, v47, vcc
	v_cmp_lt_u32_e32 vcc, s85, v58
	v_add_u32_e32 v58, 0xbfffffc6, v193
	s_nop 0
	v_cndmask_b32_e32 v32, v16, v32, vcc
	v_cmp_lt_u32_e32 vcc, s85, v58
	v_add_u32_e32 v58, 0xbfffffe5, v193
	s_nop 0
	v_cndmask_b32_e32 v48, v16, v48, vcc
	v_cmp_lt_u32_e32 vcc, s85, v58
	v_add_u32_e32 v58, 0xbfffffc5, v193
	s_nop 0
	v_cndmask_b32_e32 v33, v16, v33, vcc
	v_cmp_lt_u32_e32 vcc, s85, v58
	s_nop 1
	v_cndmask_b32_e32 v49, v16, v49, vcc
